# out-projection epilogues: per-row sum-of-squares atomics issued in batches at the end instead of after each row group
# speedup vs baseline: 1.0090x; 1.0053x over previous
;     __device__ __forceinline__ void operator()(f32x4 (&acc)[2][2][4][2], const Unit& u, int wr, int wc, int fr, int fq) const {
;         const int row0 = u.pm * BM + wr * 64 + fr, col0 = u.pn * BM + wc * 32 + 4 * fq;
; #pragma unroll
;         for (int ai = 0; ai < 2; ++ai)
; #pragma unroll
;             for (int m = 0; m < 4; ++m) { const int row = row0 + ai * HALF + m * 16; const size_t off = (size_t)row * 2048 + col0; float ss = 0.f;
; #pragma unroll
;                 for (int bj = 0; bj < 2; ++bj)
; #pragma unroll
;                     for (int n = 0; n < 2; ++n) { const f32x4 xo = *(const f32x4*)(Xin + off + bj * HALF + n * 16) + acc[ai][bj][m][n]; acc[ai][bj][m][n] = xo;
;                         if (!FINAL) *(f32x4*)(X + off + bj * HALF + n * 16) = xo;
;                         ss += (xo[0] * xo[0] + xo[1] * xo[1]) + (xo[2] * xo[2] + xo[3] * xo[3]); }
;                 ss += __shfl_xor(ss, 16); ss += __shfl_xor(ss, 32);
;                 if (fq == 0) atomicAdd(ssq + row, ss); }
.LBB0_913:
	v_lshl_add_u32 v154, s13, 8, v178
	v_lshl_or_b32 v156, s34, 8, v180
	v_ashrrev_i32_e32 v155, 31, v154
	v_ashrrev_i32_e32 v157, 31, v156
	v_lshlrev_b64 v[152:153], 11, v[154:155]
	v_lshl_add_u64 v[152:153], v[152:153], 0, v[156:157]
	v_lshlrev_b64 v[152:153], 2, v[152:153]
	v_lshl_add_u64 v[162:163], s[14:15], 0, v[152:153]
	global_load_dwordx4 v[158:161], v[162:163], off
	global_load_dwordx4 v[196:199], v[162:163], off offset:64
	global_load_dwordx4 v[200:203], v[162:163], off offset:512
	global_load_dwordx4 v[204:207], v[162:163], off offset:576
	v_lshl_add_u64 v[152:153], s[58:59], 0, v[152:153]
	s_waitcnt vmcnt(0)
	v_pk_add_f32 v[76:77], v[76:77], v[160:161]
	v_pk_add_f32 v[74:75], v[74:75], v[158:159]
	global_store_dwordx4 v[152:153], v[74:77], off
	v_mul_f32_e32 v164, v77, v77
	v_fmac_f32_e32 v164, v76, v76
	v_pk_add_f32 v[80:81], v[80:81], v[198:199]
	v_pk_add_f32 v[78:79], v[78:79], v[196:197]
	global_store_dwordx4 v[152:153], v[78:81], off offset:64
	v_mul_f32_e32 v165, v81, v81
	v_fmac_f32_e32 v165, v80, v80
	v_pk_add_f32 v[84:85], v[84:85], v[202:203]
	v_pk_add_f32 v[82:83], v[82:83], v[200:201]
	global_store_dwordx4 v[152:153], v[82:85], off offset:512
	v_and_b32_e32 v163, 64, v241
	v_xor_b32_e32 v162, 16, v241
	v_add_u32_e32 v163, 64, v163
	v_cmp_lt_i32_e32 vcc, v162, v163
	v_pk_add_f32 v[96:97], v[96:97], v[206:207]
	v_cndmask_b32_e32 v162, v241, v162, vcc
	v_lshlrev_b32_e32 v182, 2, v162
	v_mul_f32_e32 v162, v75, v75
	v_fmac_f32_e32 v162, v74, v74
	v_add_f32_e32 v162, v162, v164
	v_mul_f32_e32 v164, v79, v79
	v_fmac_f32_e32 v164, v78, v78
	v_add_f32_e32 v164, v164, v165
	v_add_f32_e32 v162, v162, v164
	v_mul_f32_e32 v164, v83, v83
	v_mul_f32_e32 v165, v85, v85
	v_pk_add_f32 v[94:95], v[94:95], v[204:205]
	v_fmac_f32_e32 v164, v82, v82
	v_fmac_f32_e32 v165, v84, v84
	v_mul_f32_e32 v158, v95, v95
	v_mul_f32_e32 v159, v97, v97
	v_add_f32_e32 v164, v164, v165
	v_fmac_f32_e32 v158, v94, v94
	v_fmac_f32_e32 v159, v96, v96
	v_add_f32_e32 v162, v162, v164
	v_add_f32_e32 v158, v158, v159
	v_add_f32_e32 v158, v162, v158
	ds_bpermute_b32 v159, v182, v158
	v_xor_b32_e32 v160, 32, v241
	v_cmp_lt_i32_e32 vcc, v160, v163
	global_store_dwordx4 v[152:153], v[94:97], off offset:576
	v_lshl_add_u64 v[152:153], v[154:155], 2, s[16:17]
	v_cndmask_b32_e32 v160, v241, v160, vcc
	v_lshlrev_b32_e32 v183, 2, v160
	s_waitcnt lgkmcnt(0)
	v_add_f32_e32 v158, v158, v159
	ds_bpermute_b32 v159, v183, v158
	s_and_saveexec_b64 s[0:1], s[4:5]
	s_mov_b32 s81, 0x2d400000
	s_cbranch_execz .LBB0_915
	s_waitcnt lgkmcnt(0)
	v_add_f32_e32 v158, v158, v159
	v_mov_b32_e32 v193, v158
.LBB0_915:
	s_or_b64 exec, exec, s[0:1]
	v_or_b32_e32 v158, 16, v154
	s_waitcnt lgkmcnt(0)
	v_ashrrev_i32_e32 v159, 31, v158
	v_lshlrev_b64 v[160:161], 11, v[158:159]
	v_lshl_add_u64 v[160:161], v[160:161], 0, v[156:157]
	v_lshlrev_b64 v[164:165], 2, v[160:161]
	v_lshl_add_u64 v[166:167], s[14:15], 0, v[164:165]
	global_load_dwordx4 v[160:163], v[166:167], off
	global_load_dwordx4 v[196:199], v[166:167], off offset:64
	global_load_dwordx4 v[200:203], v[166:167], off offset:512
	global_load_dwordx4 v[204:207], v[166:167], off offset:576
	v_lshl_add_u64 v[164:165], s[58:59], 0, v[164:165]
	s_waitcnt vmcnt(0)
	v_pk_add_f32 v[104:105], v[104:105], v[162:163]
	v_pk_add_f32 v[102:103], v[102:103], v[160:161]
	global_store_dwordx4 v[164:165], v[102:105], off
	v_pk_add_f32 v[108:109], v[108:109], v[198:199]
	v_pk_add_f32 v[106:107], v[106:107], v[196:197]
	global_store_dwordx4 v[164:165], v[106:109], off offset:64
	v_mul_f32_e32 v168, v109, v109
	v_fmac_f32_e32 v168, v108, v108
	v_pk_add_f32 v[112:113], v[112:113], v[202:203]
	v_pk_add_f32 v[110:111], v[110:111], v[200:201]
	global_store_dwordx4 v[164:165], v[110:113], off offset:512
	v_mul_f32_e32 v166, v103, v103
	v_mul_f32_e32 v167, v105, v105
	v_fmac_f32_e32 v166, v102, v102
	v_fmac_f32_e32 v167, v104, v104
	v_add_f32_e32 v166, v166, v167
	v_mul_f32_e32 v167, v107, v107
	v_fmac_f32_e32 v167, v106, v106
	v_add_f32_e32 v167, v167, v168
	v_add_f32_e32 v166, v166, v167
	v_mul_f32_e32 v167, v111, v111
	v_mul_f32_e32 v168, v113, v113
	v_fmac_f32_e32 v167, v110, v110
	v_fmac_f32_e32 v168, v112, v112
	v_add_f32_e32 v167, v167, v168
	v_add_f32_e32 v166, v166, v167
	v_pk_add_f32 v[120:121], v[120:121], v[206:207]
	v_pk_add_f32 v[118:119], v[118:119], v[204:205]
	v_mul_f32_e32 v161, v121, v121
	v_mul_f32_e32 v160, v119, v119
	v_fmac_f32_e32 v160, v118, v118
	v_fmac_f32_e32 v161, v120, v120
	v_add_f32_e32 v160, v160, v161
	v_add_f32_e32 v160, v166, v160
	ds_bpermute_b32 v161, v182, v160
	v_lshl_add_u64 v[162:163], v[158:159], 2, s[16:17]
	global_store_dwordx4 v[164:165], v[118:121], off offset:576
	s_waitcnt lgkmcnt(0)
	v_add_f32_e32 v160, v160, v161
	ds_bpermute_b32 v161, v183, v160
	s_and_saveexec_b64 s[0:1], s[4:5]
	s_cbranch_execz .LBB0_917
	s_waitcnt lgkmcnt(0)
	v_add_f32_e32 v160, v160, v161
	v_mov_b32_e32 v194, v160
;     __device__ __forceinline__ void operator()(f32x4 (&acc)[2][2][4][2], const Unit& u, int wr, int wc, int fr, int fq) const {
;     ...
;             for (int m = 0; m < 4; ++m) { const int row = row0 + ai * HALF + m * 16; const size_t off = (size_t)row * 2048 + col0; float ss = 0.f;
; #pragma unroll
;                 for (int bj = 0; bj < 2; ++bj)
; #pragma unroll
;                     for (int n = 0; n < 2; ++n) { const f32x4 xo = *(const f32x4*)(Xin + off + bj * HALF + n * 16) + acc[ai][bj][m][n]; acc[ai][bj][m][n] = xo;
;                         if (!FINAL) *(f32x4*)(X + off + bj * HALF + n * 16) = xo;
;                         ss += (xo[0] * xo[0] + xo[1] * xo[1]) + (xo[2] * xo[2] + xo[3] * xo[3]); }
;                 ss += __shfl_xor(ss, 16); ss += __shfl_xor(ss, 32);
;                 if (fq == 0) atomicAdd(ssq + row, ss); }
.LBB0_917:
	s_or_b64 exec, exec, s[0:1]
	v_or_b32_e32 v160, 32, v154
	s_waitcnt lgkmcnt(0)
	v_ashrrev_i32_e32 v161, 31, v160
	v_lshlrev_b64 v[164:165], 11, v[160:161]
	v_lshl_add_u64 v[164:165], v[164:165], 0, v[156:157]
	v_lshlrev_b64 v[168:169], 2, v[164:165]
	v_lshl_add_u64 v[170:171], s[14:15], 0, v[168:169]
	global_load_dwordx4 v[164:167], v[170:171], off
	global_load_dwordx4 v[196:199], v[170:171], off offset:64
	global_load_dwordx4 v[200:203], v[170:171], off offset:512
	global_load_dwordx4 v[204:207], v[170:171], off offset:576
	v_lshl_add_u64 v[168:169], s[58:59], 0, v[168:169]
	s_waitcnt vmcnt(0)
	v_pk_add_f32 v[124:125], v[124:125], v[166:167]
	v_pk_add_f32 v[122:123], v[122:123], v[164:165]
	global_store_dwordx4 v[168:169], v[122:125], off
	v_pk_add_f32 v[146:147], v[146:147], v[198:199]
	v_pk_add_f32 v[144:145], v[144:145], v[196:197]
	global_store_dwordx4 v[168:169], v[144:147], off offset:64
	v_mul_f32_e32 v172, v147, v147
	v_fmac_f32_e32 v172, v146, v146
	v_pk_add_f32 v[116:117], v[116:117], v[202:203]
	v_pk_add_f32 v[114:115], v[114:115], v[200:201]
	global_store_dwordx4 v[168:169], v[114:117], off offset:512
	v_mul_f32_e32 v170, v123, v123
	v_mul_f32_e32 v171, v125, v125
	v_fmac_f32_e32 v170, v122, v122
	v_fmac_f32_e32 v171, v124, v124
	v_add_f32_e32 v170, v170, v171
	v_mul_f32_e32 v171, v145, v145
	v_fmac_f32_e32 v171, v144, v144
	v_add_f32_e32 v171, v171, v172
	v_add_f32_e32 v170, v170, v171
	v_mul_f32_e32 v171, v115, v115
	v_mul_f32_e32 v172, v117, v117
	v_fmac_f32_e32 v171, v114, v114
	v_fmac_f32_e32 v172, v116, v116
	v_add_f32_e32 v171, v171, v172
	v_add_f32_e32 v170, v170, v171
	v_pk_add_f32 v[100:101], v[100:101], v[206:207]
	v_pk_add_f32 v[98:99], v[98:99], v[204:205]
	v_mul_f32_e32 v165, v101, v101
	v_mul_f32_e32 v164, v99, v99
	v_fmac_f32_e32 v164, v98, v98
	v_fmac_f32_e32 v165, v100, v100
	v_add_f32_e32 v164, v164, v165
	v_add_f32_e32 v164, v170, v164
	ds_bpermute_b32 v165, v182, v164
	v_lshl_add_u64 v[166:167], v[160:161], 2, s[16:17]
	global_store_dwordx4 v[168:169], v[98:101], off offset:576
	s_waitcnt lgkmcnt(0)
	v_add_f32_e32 v164, v164, v165
	ds_bpermute_b32 v165, v183, v164
	s_and_saveexec_b64 s[0:1], s[4:5]
	s_mov_b32 s91, 0xca00000
	s_cbranch_execz .LBB0_919
	s_waitcnt lgkmcnt(0)
	v_add_f32_e32 v164, v164, v165
	v_mov_b32_e32 v195, v164
.LBB0_919:
	s_or_b64 exec, exec, s[0:1]
	v_or_b32_e32 v164, 48, v154
	s_waitcnt lgkmcnt(0)
	v_ashrrev_i32_e32 v165, 31, v164
	v_lshlrev_b64 v[168:169], 11, v[164:165]
	v_lshl_add_u64 v[168:169], v[168:169], 0, v[156:157]
	v_lshlrev_b64 v[172:173], 2, v[168:169]
	v_lshl_add_u64 v[174:175], s[14:15], 0, v[172:173]
	global_load_dwordx4 v[168:171], v[174:175], off
	global_load_dwordx4 v[196:199], v[174:175], off offset:64
	global_load_dwordx4 v[200:203], v[174:175], off offset:512
	global_load_dwordx4 v[204:207], v[174:175], off offset:576
	v_lshl_add_u64 v[172:173], s[58:59], 0, v[172:173]
	s_waitcnt vmcnt(0)
	v_pk_add_f32 v[92:93], v[92:93], v[170:171]
	v_pk_add_f32 v[90:91], v[90:91], v[168:169]
	global_store_dwordx4 v[172:173], v[90:93], off
	v_pk_add_f32 v[88:89], v[88:89], v[198:199]
	v_pk_add_f32 v[86:87], v[86:87], v[196:197]
	global_store_dwordx4 v[172:173], v[86:89], off offset:64
	v_mul_f32_e32 v176, v89, v89
	v_fmac_f32_e32 v176, v88, v88
	v_pk_add_f32 v[72:73], v[72:73], v[202:203]
	v_pk_add_f32 v[70:71], v[70:71], v[200:201]
	global_store_dwordx4 v[172:173], v[70:73], off offset:512
	v_mul_f32_e32 v174, v91, v91
	v_mul_f32_e32 v175, v93, v93
	v_fmac_f32_e32 v174, v90, v90
	v_fmac_f32_e32 v175, v92, v92
	v_add_f32_e32 v174, v174, v175
	v_mul_f32_e32 v175, v87, v87
	v_fmac_f32_e32 v175, v86, v86
	v_add_f32_e32 v175, v175, v176
	v_add_f32_e32 v174, v174, v175
	v_mul_f32_e32 v175, v71, v71
	v_mul_f32_e32 v176, v73, v73
	v_fmac_f32_e32 v175, v70, v70
	v_fmac_f32_e32 v176, v72, v72
	v_add_f32_e32 v175, v175, v176
	v_add_f32_e32 v174, v174, v175
	v_pk_add_f32 v[68:69], v[68:69], v[206:207]
	v_pk_add_f32 v[66:67], v[66:67], v[204:205]
	v_mul_f32_e32 v169, v69, v69
	v_mul_f32_e32 v168, v67, v67
	v_fmac_f32_e32 v168, v66, v66
	v_fmac_f32_e32 v169, v68, v68
	v_add_f32_e32 v168, v168, v169
	v_add_f32_e32 v168, v174, v168
	ds_bpermute_b32 v169, v182, v168
	v_lshl_add_u64 v[170:171], v[164:165], 2, s[16:17]
	global_store_dwordx4 v[172:173], v[66:69], off offset:576
	s_waitcnt lgkmcnt(0)
	v_add_f32_e32 v168, v168, v169
	ds_bpermute_b32 v169, v183, v168
	s_and_saveexec_b64 s[0:1], s[4:5]
	s_cbranch_execz .LBB0_921
	s_waitcnt lgkmcnt(0)
	v_add_f32_e32 v168, v168, v169
	v_mov_b32_e32 v216, v168
;     __device__ __forceinline__ void operator()(f32x4 (&acc)[2][2][4][2], const Unit& u, int wr, int wc, int fr, int fq) const {
;     ...
;             for (int m = 0; m < 4; ++m) { const int row = row0 + ai * HALF + m * 16; const size_t off = (size_t)row * 2048 + col0; float ss = 0.f;
; #pragma unroll
;                 for (int bj = 0; bj < 2; ++bj)
; #pragma unroll
;                     for (int n = 0; n < 2; ++n) { const f32x4 xo = *(const f32x4*)(Xin + off + bj * HALF + n * 16) + acc[ai][bj][m][n]; acc[ai][bj][m][n] = xo;
;                         if (!FINAL) *(f32x4*)(X + off + bj * HALF + n * 16) = xo;
;                         ss += (xo[0] * xo[0] + xo[1] * xo[1]) + (xo[2] * xo[2] + xo[3] * xo[3]); }
;                 ss += __shfl_xor(ss, 16); ss += __shfl_xor(ss, 32);
;                 if (fq == 0) atomicAdd(ssq + row, ss); }
.LBB0_921:
	s_or_b64 exec, exec, s[0:1]
	v_add_u32_e32 v168, 0x80, v154
	s_waitcnt lgkmcnt(0)
	v_ashrrev_i32_e32 v169, 31, v168
	v_lshlrev_b64 v[172:173], 11, v[168:169]
	v_lshl_add_u64 v[172:173], v[172:173], 0, v[156:157]
	v_lshlrev_b64 v[176:177], 2, v[172:173]
	v_lshl_add_u64 v[184:185], s[14:15], 0, v[176:177]
	global_load_dwordx4 v[172:175], v[184:185], off
	global_load_dwordx4 v[196:199], v[184:185], off offset:64
	global_load_dwordx4 v[200:203], v[184:185], off offset:512
	global_load_dwordx4 v[204:207], v[184:185], off offset:576
	v_lshl_add_u64 v[176:177], s[58:59], 0, v[176:177]
	s_waitcnt vmcnt(0)
	v_pk_add_f32 v[64:65], v[64:65], v[174:175]
	v_pk_add_f32 v[62:63], v[62:63], v[172:173]
	global_store_dwordx4 v[176:177], v[62:65], off
	v_pk_add_f32 v[60:61], v[60:61], v[198:199]
	v_pk_add_f32 v[58:59], v[58:59], v[196:197]
	global_store_dwordx4 v[176:177], v[58:61], off offset:64
	v_mul_f32_e32 v186, v61, v61
	v_fmac_f32_e32 v186, v60, v60
	v_pk_add_f32 v[56:57], v[56:57], v[202:203]
	v_pk_add_f32 v[54:55], v[54:55], v[200:201]
	global_store_dwordx4 v[176:177], v[54:57], off offset:512
	v_mul_f32_e32 v184, v63, v63
	v_mul_f32_e32 v185, v65, v65
	v_fmac_f32_e32 v184, v62, v62
	v_fmac_f32_e32 v185, v64, v64
	v_add_f32_e32 v184, v184, v185
	v_mul_f32_e32 v185, v59, v59
	v_fmac_f32_e32 v185, v58, v58
	v_add_f32_e32 v185, v185, v186
	v_add_f32_e32 v184, v184, v185
	v_mul_f32_e32 v185, v55, v55
	v_mul_f32_e32 v186, v57, v57
	v_fmac_f32_e32 v185, v54, v54
	v_fmac_f32_e32 v186, v56, v56
	v_add_f32_e32 v185, v185, v186
	v_add_f32_e32 v184, v184, v185
	v_pk_add_f32 v[52:53], v[52:53], v[206:207]
	v_pk_add_f32 v[50:51], v[50:51], v[204:205]
	v_mul_f32_e32 v173, v53, v53
	v_mul_f32_e32 v172, v51, v51
	v_fmac_f32_e32 v172, v50, v50
	v_fmac_f32_e32 v173, v52, v52
	v_add_f32_e32 v172, v172, v173
	v_add_f32_e32 v172, v184, v172
	ds_bpermute_b32 v173, v182, v172
	global_store_dwordx4 v[176:177], v[50:53], off offset:576
	s_waitcnt lgkmcnt(0)
	v_add_f32_e32 v172, v172, v173
	ds_bpermute_b32 v173, v183, v172
	s_and_saveexec_b64 s[0:1], s[4:5]
	s_cbranch_execz .LBB0_923
	v_lshl_add_u64 v[174:175], v[168:169], 2, s[16:17]
	s_waitcnt lgkmcnt(0)
	v_add_f32_e32 v172, v172, v173
	v_mov_b32_e32 v217, v172
.LBB0_923:
	s_or_b64 exec, exec, s[0:1]
	v_add_u32_e32 v172, 0x90, v154
	s_waitcnt lgkmcnt(0)
	v_ashrrev_i32_e32 v173, 31, v172
	v_lshlrev_b64 v[174:175], 11, v[172:173]
	v_lshl_add_u64 v[174:175], v[174:175], 0, v[156:157]
	v_lshlrev_b64 v[184:185], 2, v[174:175]
	v_lshl_add_u64 v[186:187], s[14:15], 0, v[184:185]
	global_load_dwordx4 v[174:177], v[186:187], off
	global_load_dwordx4 v[196:199], v[186:187], off offset:64
	global_load_dwordx4 v[200:203], v[186:187], off offset:512
	global_load_dwordx4 v[204:207], v[186:187], off offset:576
	v_lshl_add_u64 v[184:185], s[58:59], 0, v[184:185]
	s_waitcnt vmcnt(0)
	v_pk_add_f32 v[48:49], v[48:49], v[176:177]
	v_pk_add_f32 v[46:47], v[46:47], v[174:175]
	global_store_dwordx4 v[184:185], v[46:49], off
	v_pk_add_f32 v[44:45], v[44:45], v[198:199]
	v_pk_add_f32 v[42:43], v[42:43], v[196:197]
	global_store_dwordx4 v[184:185], v[42:45], off offset:64
	v_mul_f32_e32 v188, v45, v45
	v_fmac_f32_e32 v188, v44, v44
	v_pk_add_f32 v[40:41], v[40:41], v[202:203]
	v_pk_add_f32 v[38:39], v[38:39], v[200:201]
	global_store_dwordx4 v[184:185], v[38:41], off offset:512
	v_mul_f32_e32 v186, v47, v47
	v_mul_f32_e32 v187, v49, v49
	v_fmac_f32_e32 v186, v46, v46
	v_fmac_f32_e32 v187, v48, v48
	v_add_f32_e32 v186, v186, v187
	v_mul_f32_e32 v187, v43, v43
	v_fmac_f32_e32 v187, v42, v42
	v_add_f32_e32 v187, v187, v188
	v_add_f32_e32 v186, v186, v187
	v_mul_f32_e32 v187, v39, v39
	v_mul_f32_e32 v188, v41, v41
	v_fmac_f32_e32 v187, v38, v38
	v_fmac_f32_e32 v188, v40, v40
	v_add_f32_e32 v187, v187, v188
	v_add_f32_e32 v186, v186, v187
	v_pk_add_f32 v[36:37], v[36:37], v[206:207]
	v_pk_add_f32 v[34:35], v[34:35], v[204:205]
	v_mul_f32_e32 v175, v37, v37
	v_mul_f32_e32 v174, v35, v35
	v_fmac_f32_e32 v174, v34, v34
	v_fmac_f32_e32 v175, v36, v36
	v_add_f32_e32 v174, v174, v175
	v_add_f32_e32 v174, v186, v174
	ds_bpermute_b32 v175, v182, v174
	global_store_dwordx4 v[184:185], v[34:37], off offset:576
	s_waitcnt lgkmcnt(0)
	v_add_f32_e32 v174, v174, v175
	ds_bpermute_b32 v175, v183, v174
	s_and_saveexec_b64 s[0:1], s[4:5]
	s_cbranch_execz .LBB0_925
	v_lshl_add_u64 v[176:177], v[172:173], 2, s[16:17]
	s_waitcnt lgkmcnt(0)
	v_add_f32_e32 v174, v174, v175
	v_mov_b32_e32 v224, v174
;     __device__ __forceinline__ void operator()(f32x4 (&acc)[2][2][4][2], const Unit& u, int wr, int wc, int fr, int fq) const {
;     ...
;             for (int m = 0; m < 4; ++m) { const int row = row0 + ai * HALF + m * 16; const size_t off = (size_t)row * 2048 + col0; float ss = 0.f;
; #pragma unroll
;                 for (int bj = 0; bj < 2; ++bj)
; #pragma unroll
;                     for (int n = 0; n < 2; ++n) { const f32x4 xo = *(const f32x4*)(Xin + off + bj * HALF + n * 16) + acc[ai][bj][m][n]; acc[ai][bj][m][n] = xo;
;                         if (!FINAL) *(f32x4*)(X + off + bj * HALF + n * 16) = xo;
;                         ss += (xo[0] * xo[0] + xo[1] * xo[1]) + (xo[2] * xo[2] + xo[3] * xo[3]); }
;                 ss += __shfl_xor(ss, 16); ss += __shfl_xor(ss, 32);
;                 if (fq == 0) atomicAdd(ssq + row, ss); }
;         asm volatile("s_waitcnt vmcnt(0)" ::: "memory");
;         __builtin_amdgcn_s_barrier();
;         if (threadIdx.x == 0) { unsigned* c = cnt + 64 * u.pm; __hip_atomic_fetch_add(c, 1u, __ATOMIC_RELAXED, __HIP_MEMORY_SCOPE_AGENT);
.LBB0_925:
	s_or_b64 exec, exec, s[0:1]
	v_add_u32_e32 v174, 0xa0, v154
	s_waitcnt lgkmcnt(0)
	v_ashrrev_i32_e32 v175, 31, v174
	v_lshlrev_b64 v[176:177], 11, v[174:175]
	v_lshl_add_u64 v[176:177], v[176:177], 0, v[156:157]
	v_lshlrev_b64 v[176:177], 2, v[176:177]
	v_lshl_add_u64 v[188:189], s[14:15], 0, v[176:177]
	global_load_dwordx4 v[184:187], v[188:189], off
	global_load_dwordx4 v[196:199], v[188:189], off offset:64
	global_load_dwordx4 v[200:203], v[188:189], off offset:512
	global_load_dwordx4 v[204:207], v[188:189], off offset:576
	v_lshl_add_u64 v[190:191], s[58:59], 0, v[176:177]
	s_waitcnt vmcnt(0)
	v_pk_add_f32 v[32:33], v[32:33], v[186:187]
	v_pk_add_f32 v[30:31], v[30:31], v[184:185]
	global_store_dwordx4 v[190:191], v[30:33], off
	v_mul_f32_e32 v176, v31, v31
	v_mul_f32_e32 v177, v33, v33
	v_fmac_f32_e32 v176, v30, v30
	v_fmac_f32_e32 v177, v32, v32
	v_add_f32_e32 v176, v176, v177
	v_pk_add_f32 v[28:29], v[28:29], v[198:199]
	v_pk_add_f32 v[26:27], v[26:27], v[196:197]
	global_store_dwordx4 v[190:191], v[26:29], off offset:64
	v_mul_f32_e32 v177, v27, v27
	v_fmac_f32_e32 v177, v26, v26
	v_pk_add_f32 v[24:25], v[24:25], v[202:203]
	v_pk_add_f32 v[22:23], v[22:23], v[200:201]
	global_store_dwordx4 v[190:191], v[22:25], off offset:512
	v_mul_f32_e32 v188, v29, v29
	v_fmac_f32_e32 v188, v28, v28
	v_add_f32_e32 v177, v177, v188
	v_add_f32_e32 v176, v176, v177
	v_mul_f32_e32 v177, v23, v23
	v_mul_f32_e32 v188, v25, v25
	v_fmac_f32_e32 v177, v22, v22
	v_fmac_f32_e32 v188, v24, v24
	v_add_f32_e32 v177, v177, v188
	v_add_f32_e32 v176, v176, v177
	v_pk_add_f32 v[20:21], v[20:21], v[206:207]
	v_pk_add_f32 v[18:19], v[18:19], v[204:205]
	v_mul_f32_e32 v184, v21, v21
	v_mul_f32_e32 v177, v19, v19
	v_fmac_f32_e32 v177, v18, v18
	v_fmac_f32_e32 v184, v20, v20
	v_add_f32_e32 v177, v177, v184
	v_add_f32_e32 v176, v176, v177
	ds_bpermute_b32 v177, v182, v176
	global_store_dwordx4 v[190:191], v[18:21], off offset:576
	s_waitcnt lgkmcnt(0)
	v_add_f32_e32 v176, v176, v177
	ds_bpermute_b32 v177, v183, v176
	s_and_saveexec_b64 s[0:1], s[4:5]
	s_cbranch_execz .LBB0_927
	v_lshl_add_u64 v[184:185], v[174:175], 2, s[16:17]
	s_waitcnt lgkmcnt(0)
	v_add_f32_e32 v176, v176, v177
	v_mov_b32_e32 v225, v176
.LBB0_927:
	s_or_b64 exec, exec, s[0:1]
	v_add_u32_e32 v176, 0xb0, v154
	s_waitcnt lgkmcnt(0)
	v_ashrrev_i32_e32 v177, 31, v176
	v_lshlrev_b64 v[184:185], 11, v[176:177]
	v_lshl_add_u64 v[184:185], v[184:185], 0, v[156:157]
	v_lshlrev_b64 v[188:189], 2, v[184:185]
	v_lshl_add_u64 v[190:191], s[14:15], 0, v[188:189]
	global_load_dwordx4 v[184:187], v[190:191], off
	global_load_dwordx4 v[196:199], v[190:191], off offset:64
	global_load_dwordx4 v[200:203], v[190:191], off offset:512
	global_load_dwordx4 v[204:207], v[190:191], off offset:576
	v_lshl_add_u64 v[188:189], s[58:59], 0, v[188:189]
	s_waitcnt vmcnt(0)
	v_pk_add_f32 v[16:17], v[16:17], v[186:187]
	v_pk_add_f32 v[14:15], v[14:15], v[184:185]
	global_store_dwordx4 v[188:189], v[14:17], off
	v_pk_add_f32 v[12:13], v[12:13], v[198:199]
	v_pk_add_f32 v[10:11], v[10:11], v[196:197]
	global_store_dwordx4 v[188:189], v[10:13], off offset:64
	v_mul_f32_e32 v192, v13, v13
	v_fmac_f32_e32 v192, v12, v12
	v_pk_add_f32 v[8:9], v[8:9], v[202:203]
	v_pk_add_f32 v[6:7], v[6:7], v[200:201]
	global_store_dwordx4 v[188:189], v[6:9], off offset:512
	v_mul_f32_e32 v190, v15, v15
	v_mul_f32_e32 v191, v17, v17
	v_fmac_f32_e32 v190, v14, v14
	v_fmac_f32_e32 v191, v16, v16
	v_add_f32_e32 v190, v190, v191
	v_mul_f32_e32 v191, v11, v11
	v_fmac_f32_e32 v191, v10, v10
	v_add_f32_e32 v191, v191, v192
	v_add_f32_e32 v190, v190, v191
	v_mul_f32_e32 v191, v7, v7
	v_mul_f32_e32 v192, v9, v9
	v_fmac_f32_e32 v191, v6, v6
	v_fmac_f32_e32 v192, v8, v8
	v_add_f32_e32 v191, v191, v192
	v_add_f32_e32 v190, v190, v191
	v_pk_add_f32 v[4:5], v[4:5], v[206:207]
	v_pk_add_f32 v[2:3], v[2:3], v[204:205]
	v_mul_f32_e32 v185, v5, v5
	v_mul_f32_e32 v184, v3, v3
	v_fmac_f32_e32 v184, v2, v2
	v_fmac_f32_e32 v185, v4, v4
	v_add_f32_e32 v184, v184, v185
	v_add_f32_e32 v184, v190, v184
	ds_bpermute_b32 v182, v182, v184
	global_store_dwordx4 v[188:189], v[2:5], off offset:576
	s_waitcnt lgkmcnt(0)
	v_add_f32_e32 v182, v184, v182
	ds_bpermute_b32 v183, v183, v182
	s_and_saveexec_b64 s[0:1], s[4:5]
	s_cbranch_execz .LBB0_929
	v_lshl_add_u64 v[184:185], v[176:177], 2, s[16:17]
	s_waitcnt lgkmcnt(0)
	v_add_f32_e32 v182, v182, v183
	v_mov_b32_e32 v226, v182
.LBB0_929:
	s_or_b64 exec, exec, s[0:1]
	s_and_saveexec_b64 s[0:1], s[4:5]
	global_atomic_add_f32 v[152:153], v193, off
	global_atomic_add_f32 v[162:163], v194, off
	global_atomic_add_f32 v[166:167], v195, off
	global_atomic_add_f32 v[170:171], v216, off
	global_atomic_add_f32 v[152:153], v217, off offset:512
	global_atomic_add_f32 v[152:153], v224, off offset:576
	global_atomic_add_f32 v[152:153], v225, off offset:640
	global_atomic_add_f32 v[152:153], v226, off offset:704
	s_or_b64 exec, exec, s[0:1]
	s_waitcnt vmcnt(0)
	s_barrier
	s_mov_b64 s[0:1], exec
	v_readlane_b32 s28, v253, 7
	v_readlane_b32 s29, v253, 8
	s_and_b64 s[28:29], s[0:1], s[28:29]
	s_mov_b64 exec, s[28:29]
	s_cbranch_execz .LBB0_944
	s_lshl_b32 s28, s13, 6
	s_mov_b64 s[30:31], exec
	s_ashr_i32 s29, s28, 31
	s_lshl_b64 s[28:29], s[28:29], 2
	v_mbcnt_lo_u32_b32 v182, s30, 0
	s_add_u32 s28, s84, s28
	v_mbcnt_hi_u32_b32 v182, s31, v182
	s_addc_u32 s29, s85, s29
	v_cmp_eq_u32_e32 vcc, 0, v182
	s_and_saveexec_b64 s[34:35], vcc
	s_cbranch_execz .LBB0_932
	s_bcnt1_i32_b64 s13, s[30:31]
	v_mov_b32_e32 v182, s13
	global_atomic_add v1, v182, s[28:29]

;     __device__ __forceinline__ void operator()(f32x4 (&acc)[2][2][4][2], const Unit& u, int wr, int wc, int fr, int fq) const {
;         const int row0 = u.pm * BM + wr * 64 + fr, col0 = u.pn * BM + wc * 32 + 4 * fq;
; #pragma unroll
;         for (int ai = 0; ai < 2; ++ai)
; #pragma unroll
;             for (int m = 0; m < 4; ++m) { const int row = row0 + ai * HALF + m * 16; const size_t off = (size_t)row * 2048 + col0; float ss = 0.f;
; #pragma unroll
;                 for (int bj = 0; bj < 2; ++bj)
; #pragma unroll
;                     for (int n = 0; n < 2; ++n) { const f32x4 xo = *(const f32x4*)(Xin + off + bj * HALF + n * 16) + acc[ai][bj][m][n]; acc[ai][bj][m][n] = xo;
;                         if (!FINAL) *(f32x4*)(X + off + bj * HALF + n * 16) = xo;
;                         ss += (xo[0] * xo[0] + xo[1] * xo[1]) + (xo[2] * xo[2] + xo[3] * xo[3]); }
;                 ss += __shfl_xor(ss, 16); ss += __shfl_xor(ss, 32);
;                 if (fq == 0) atomicAdd(ssq + row, ss); }
.LBB0_966:
	v_and_b32_e32 v153, 64, v241
	v_xor_b32_e32 v152, 16, v241
	v_add_u32_e32 v153, 64, v153
	v_cmp_lt_i32_e32 vcc, v152, v153
	v_lshl_add_u32 v162, s28, 8, v196
	v_ashrrev_i32_e32 v163, 31, v162
	v_cndmask_b32_e32 v152, v241, v152, vcc
	v_lshlrev_b32_e32 v200, 2, v152
	v_xor_b32_e32 v152, 32, v241
	v_cmp_lt_i32_e32 vcc, v152, v153
	v_lshl_or_b32 v154, s12, 8, v198
	v_ashrrev_i32_e32 v155, 31, v154
	v_cndmask_b32_e32 v152, v241, v152, vcc
	v_lshlrev_b32_e32 v201, 2, v152
	v_lshlrev_b64 v[152:153], 13, v[162:163]
	v_lshl_add_u64 v[152:153], s[58:59], 0, v[152:153]
	v_lshl_add_u64 v[152:153], v[154:155], 2, v[152:153]
	global_load_dwordx4 v[156:159], v[152:153], off
	global_load_dwordx4 v[204:207], v[152:153], off offset:64
	global_load_dwordx4 v[208:211], v[152:153], off offset:512
	global_load_dwordx4 v[212:215], v[152:153], off offset:576
	v_readlane_b32 s0, v253, 30
	v_readlane_b32 s1, v253, 31
	s_waitcnt vmcnt(3)
	v_pk_add_f32 v[146:147], v[146:147], v[158:159]
	v_pk_add_f32 v[144:145], v[144:145], v[156:157]
	v_mul_f32_e32 v157, v147, v147
	v_mul_f32_e32 v156, v145, v145
	v_fmac_f32_e32 v156, v144, v144
	v_fmac_f32_e32 v157, v146, v146
	v_add_f32_e32 v160, v156, v157
	s_waitcnt vmcnt(2)
	v_pk_add_f32 v[124:125], v[124:125], v[206:207]
	v_pk_add_f32 v[122:123], v[122:123], v[204:205]
	v_mul_f32_e32 v157, v125, v125
	v_mul_f32_e32 v156, v123, v123
	v_fmac_f32_e32 v156, v122, v122
	v_fmac_f32_e32 v157, v124, v124
	v_add_f32_e32 v156, v156, v157
	v_add_f32_e32 v160, v160, v156
	s_waitcnt vmcnt(1)
	v_pk_add_f32 v[120:121], v[120:121], v[210:211]
	v_pk_add_f32 v[118:119], v[118:119], v[208:209]
	v_mul_f32_e32 v157, v121, v121
	v_mul_f32_e32 v156, v119, v119
	v_fmac_f32_e32 v156, v118, v118
	v_fmac_f32_e32 v157, v120, v120
	v_add_f32_e32 v156, v156, v157
	v_add_f32_e32 v160, v160, v156
	s_waitcnt vmcnt(0)
	v_pk_add_f32 v[116:117], v[116:117], v[214:215]
	v_pk_add_f32 v[156:157], v[114:115], v[212:213]
	v_mul_f32_e32 v115, v117, v117
	v_mul_f32_e32 v114, v157, v157
	v_fmac_f32_e32 v114, v156, v156
	v_fmac_f32_e32 v115, v116, v116
	v_add_f32_e32 v114, v114, v115
	v_add_f32_e32 v114, v160, v114
	ds_bpermute_b32 v115, v200, v114
	s_waitcnt lgkmcnt(0)
	v_add_f32_e32 v158, v114, v115
	ds_bpermute_b32 v159, v201, v158
	v_lshl_add_u64 v[114:115], v[162:163], 2, s[0:1]
	s_and_saveexec_b64 s[0:1], s[4:5]
	s_cbranch_execz .LBB0_968
	s_waitcnt lgkmcnt(0)
	v_add_f32_e32 v158, v158, v159
	v_mov_b32_e32 v216, v158
.LBB0_968:
	s_or_b64 exec, exec, s[0:1]
	v_or_b32_e32 v160, 16, v162
	v_ashrrev_i32_e32 v161, 31, v160
	s_waitcnt lgkmcnt(0)
	v_lshlrev_b64 v[158:159], 13, v[160:161]
	v_lshl_add_u64 v[158:159], s[58:59], 0, v[158:159]
	v_lshl_add_u64 v[158:159], v[154:155], 2, v[158:159]
	global_load_dwordx4 v[164:167], v[158:159], off
	global_load_dwordx4 v[204:207], v[158:159], off offset:64
	global_load_dwordx4 v[208:211], v[158:159], off offset:512
	global_load_dwordx4 v[212:215], v[158:159], off offset:576
	v_readlane_b32 s0, v253, 30
	v_readlane_b32 s1, v253, 31
	s_waitcnt vmcnt(3)
	v_pk_add_f32 v[112:113], v[112:113], v[166:167]
	v_pk_add_f32 v[110:111], v[110:111], v[164:165]
	v_mul_f32_e32 v164, v113, v113
	v_mul_f32_e32 v163, v111, v111
	v_fmac_f32_e32 v163, v110, v110
	v_fmac_f32_e32 v164, v112, v112
	v_add_f32_e32 v163, v163, v164
	s_waitcnt vmcnt(2)
	v_pk_add_f32 v[108:109], v[108:109], v[206:207]
	v_pk_add_f32 v[106:107], v[106:107], v[204:205]
	v_mul_f32_e32 v165, v109, v109
	v_mul_f32_e32 v164, v107, v107
	v_fmac_f32_e32 v164, v106, v106
	v_fmac_f32_e32 v165, v108, v108
	v_add_f32_e32 v164, v164, v165
	v_add_f32_e32 v163, v163, v164
	s_waitcnt vmcnt(1)
	v_pk_add_f32 v[104:105], v[104:105], v[210:211]
	v_pk_add_f32 v[102:103], v[102:103], v[208:209]
	v_mul_f32_e32 v165, v105, v105
	v_mul_f32_e32 v164, v103, v103
	v_fmac_f32_e32 v164, v102, v102
	v_fmac_f32_e32 v165, v104, v104
	v_add_f32_e32 v164, v164, v165
	v_add_f32_e32 v163, v163, v164
	s_waitcnt vmcnt(0)
	v_pk_add_f32 v[100:101], v[100:101], v[214:215]
	v_pk_add_f32 v[98:99], v[98:99], v[212:213]
	v_mul_f32_e32 v165, v101, v101
	v_mul_f32_e32 v164, v99, v99
	v_fmac_f32_e32 v164, v98, v98
	v_fmac_f32_e32 v165, v100, v100
	v_add_f32_e32 v164, v164, v165
	v_add_f32_e32 v163, v163, v164
	ds_bpermute_b32 v164, v200, v163
	s_waitcnt lgkmcnt(0)
	v_add_f32_e32 v163, v163, v164
	ds_bpermute_b32 v166, v201, v163
	v_lshl_add_u64 v[164:165], v[160:161], 2, s[0:1]
	s_and_saveexec_b64 s[0:1], s[4:5]
	s_cbranch_execz .LBB0_970
	s_waitcnt lgkmcnt(0)
	v_add_f32_e32 v160, v163, v166
	v_mov_b32_e32 v217, v160
.LBB0_970:
	s_or_b64 exec, exec, s[0:1]
	s_waitcnt lgkmcnt(0)
	v_or_b32_e32 v166, 32, v162
	v_ashrrev_i32_e32 v167, 31, v166
	v_lshlrev_b64 v[160:161], 13, v[166:167]
	v_lshl_add_u64 v[160:161], s[58:59], 0, v[160:161]
	v_lshl_add_u64 v[160:161], v[154:155], 2, v[160:161]
	global_load_dwordx4 v[168:171], v[160:161], off
	global_load_dwordx4 v[204:207], v[160:161], off offset:64
	global_load_dwordx4 v[208:211], v[160:161], off offset:512
	global_load_dwordx4 v[212:215], v[160:161], off offset:576
	v_readlane_b32 s0, v253, 30
	v_readlane_b32 s1, v253, 31
	s_waitcnt vmcnt(3)
	v_pk_add_f32 v[96:97], v[96:97], v[170:171]
	v_pk_add_f32 v[94:95], v[94:95], v[168:169]
	v_mul_f32_e32 v168, v97, v97
	v_mul_f32_e32 v163, v95, v95
	v_fmac_f32_e32 v163, v94, v94
	v_fmac_f32_e32 v168, v96, v96
	v_add_f32_e32 v163, v163, v168
	s_waitcnt vmcnt(2)
	v_pk_add_f32 v[92:93], v[92:93], v[206:207]
	v_pk_add_f32 v[90:91], v[90:91], v[204:205]
	v_mul_f32_e32 v169, v93, v93
	v_mul_f32_e32 v168, v91, v91
	v_fmac_f32_e32 v168, v90, v90
	v_fmac_f32_e32 v169, v92, v92
	v_add_f32_e32 v168, v168, v169
	v_add_f32_e32 v163, v163, v168
	s_waitcnt vmcnt(1)
	v_pk_add_f32 v[88:89], v[88:89], v[210:211]
	v_pk_add_f32 v[86:87], v[86:87], v[208:209]
	v_mul_f32_e32 v169, v89, v89
	v_mul_f32_e32 v168, v87, v87
	v_fmac_f32_e32 v168, v86, v86
	v_fmac_f32_e32 v169, v88, v88
	v_add_f32_e32 v168, v168, v169
	v_add_f32_e32 v163, v163, v168
	s_waitcnt vmcnt(0)
	v_pk_add_f32 v[84:85], v[84:85], v[214:215]
	v_pk_add_f32 v[82:83], v[82:83], v[212:213]
	v_mul_f32_e32 v169, v85, v85
	v_mul_f32_e32 v168, v83, v83
	v_fmac_f32_e32 v168, v82, v82
	v_fmac_f32_e32 v169, v84, v84
	v_add_f32_e32 v168, v168, v169
	v_add_f32_e32 v163, v163, v168
	ds_bpermute_b32 v168, v200, v163
	s_waitcnt lgkmcnt(0)
	v_add_f32_e32 v163, v163, v168
	ds_bpermute_b32 v170, v201, v163
	v_lshl_add_u64 v[168:169], v[166:167], 2, s[0:1]
	s_and_saveexec_b64 s[0:1], s[4:5]
	s_cbranch_execz .LBB0_972
	s_waitcnt lgkmcnt(0)
	v_add_f32_e32 v163, v163, v170
	v_mov_b32_e32 v218, v163
;     __device__ __forceinline__ void operator()(f32x4 (&acc)[2][2][4][2], const Unit& u, int wr, int wc, int fr, int fq) const {
;     ...
;             for (int m = 0; m < 4; ++m) { const int row = row0 + ai * HALF + m * 16; const size_t off = (size_t)row * 2048 + col0; float ss = 0.f;
; #pragma unroll
;                 for (int bj = 0; bj < 2; ++bj)
; #pragma unroll
;                     for (int n = 0; n < 2; ++n) { const f32x4 xo = *(const f32x4*)(Xin + off + bj * HALF + n * 16) + acc[ai][bj][m][n]; acc[ai][bj][m][n] = xo;
;                         if (!FINAL) *(f32x4*)(X + off + bj * HALF + n * 16) = xo;
;                         ss += (xo[0] * xo[0] + xo[1] * xo[1]) + (xo[2] * xo[2] + xo[3] * xo[3]); }
;                 ss += __shfl_xor(ss, 16); ss += __shfl_xor(ss, 32);
;                 if (fq == 0) atomicAdd(ssq + row, ss); }
.LBB0_972:
	s_or_b64 exec, exec, s[0:1]
	s_waitcnt lgkmcnt(0)
	v_or_b32_e32 v170, 48, v162
	v_ashrrev_i32_e32 v171, 31, v170
	v_lshlrev_b64 v[166:167], 13, v[170:171]
	v_lshl_add_u64 v[166:167], s[58:59], 0, v[166:167]
	v_lshl_add_u64 v[166:167], v[154:155], 2, v[166:167]
	global_load_dwordx4 v[172:175], v[166:167], off
	global_load_dwordx4 v[204:207], v[166:167], off offset:64
	global_load_dwordx4 v[208:211], v[166:167], off offset:512
	global_load_dwordx4 v[212:215], v[166:167], off offset:576
	v_readlane_b32 s0, v253, 30
	v_readlane_b32 s1, v253, 31
	s_waitcnt vmcnt(3)
	v_pk_add_f32 v[80:81], v[80:81], v[174:175]
	v_pk_add_f32 v[78:79], v[78:79], v[172:173]
	v_mul_f32_e32 v172, v81, v81
	v_mul_f32_e32 v163, v79, v79
	v_fmac_f32_e32 v163, v78, v78
	v_fmac_f32_e32 v172, v80, v80
	v_add_f32_e32 v163, v163, v172
	s_waitcnt vmcnt(2)
	v_pk_add_f32 v[76:77], v[76:77], v[206:207]
	v_pk_add_f32 v[74:75], v[74:75], v[204:205]
	v_mul_f32_e32 v173, v77, v77
	v_mul_f32_e32 v172, v75, v75
	v_fmac_f32_e32 v172, v74, v74
	v_fmac_f32_e32 v173, v76, v76
	v_add_f32_e32 v172, v172, v173
	v_add_f32_e32 v163, v163, v172
	s_waitcnt vmcnt(1)
	v_pk_add_f32 v[72:73], v[72:73], v[210:211]
	v_pk_add_f32 v[70:71], v[70:71], v[208:209]
	v_mul_f32_e32 v173, v73, v73
	v_mul_f32_e32 v172, v71, v71
	v_fmac_f32_e32 v172, v70, v70
	v_fmac_f32_e32 v173, v72, v72
	v_add_f32_e32 v172, v172, v173
	v_add_f32_e32 v163, v163, v172
	s_waitcnt vmcnt(0)
	v_pk_add_f32 v[68:69], v[68:69], v[214:215]
	v_pk_add_f32 v[66:67], v[66:67], v[212:213]
	v_mul_f32_e32 v173, v69, v69
	v_mul_f32_e32 v172, v67, v67
	v_fmac_f32_e32 v172, v66, v66
	v_fmac_f32_e32 v173, v68, v68
	v_add_f32_e32 v172, v172, v173
	v_add_f32_e32 v163, v163, v172
	ds_bpermute_b32 v172, v200, v163
	s_waitcnt lgkmcnt(0)
	v_add_f32_e32 v163, v163, v172
	ds_bpermute_b32 v174, v201, v163
	v_lshl_add_u64 v[172:173], v[170:171], 2, s[0:1]
	s_and_saveexec_b64 s[0:1], s[4:5]
	s_cbranch_execz .LBB0_974
	s_waitcnt lgkmcnt(0)
	v_add_f32_e32 v163, v163, v174
	v_mov_b32_e32 v219, v163
.LBB0_974:
	s_or_b64 exec, exec, s[0:1]
	s_and_saveexec_b64 s[0:1], s[4:5]
	global_atomic_add_f32 v[114:115], v216, off
	global_atomic_add_f32 v[164:165], v217, off
	global_atomic_add_f32 v[168:169], v218, off
	global_atomic_add_f32 v[172:173], v219, off
	s_or_b64 exec, exec, s[0:1]
	s_waitcnt lgkmcnt(0)
	v_add_u32_e32 v174, 0x80, v162
	v_ashrrev_i32_e32 v175, 31, v174
	v_lshlrev_b64 v[170:171], 13, v[174:175]
	v_lshl_add_u64 v[170:171], s[58:59], 0, v[170:171]
	v_lshl_add_u64 v[170:171], v[154:155], 2, v[170:171]
	global_load_dwordx4 v[176:179], v[170:171], off
	global_load_dwordx4 v[204:207], v[170:171], off offset:64
	global_load_dwordx4 v[208:211], v[170:171], off offset:512
	global_load_dwordx4 v[212:215], v[170:171], off offset:576
	s_waitcnt vmcnt(3)
	v_pk_add_f32 v[64:65], v[64:65], v[178:179]
	v_pk_add_f32 v[62:63], v[62:63], v[176:177]
	v_mul_f32_e32 v176, v65, v65
	v_mul_f32_e32 v163, v63, v63
	v_fmac_f32_e32 v163, v62, v62
	v_fmac_f32_e32 v176, v64, v64
	v_add_f32_e32 v163, v163, v176
	s_waitcnt vmcnt(2)
	v_pk_add_f32 v[60:61], v[60:61], v[206:207]
	v_pk_add_f32 v[58:59], v[58:59], v[204:205]
	v_mul_f32_e32 v177, v61, v61
	v_mul_f32_e32 v176, v59, v59
	v_fmac_f32_e32 v176, v58, v58
	v_fmac_f32_e32 v177, v60, v60
	v_add_f32_e32 v176, v176, v177
	v_add_f32_e32 v163, v163, v176
	s_waitcnt vmcnt(1)
	v_pk_add_f32 v[56:57], v[56:57], v[210:211]
	v_pk_add_f32 v[54:55], v[54:55], v[208:209]
	v_mul_f32_e32 v177, v57, v57
	v_mul_f32_e32 v176, v55, v55
	v_fmac_f32_e32 v176, v54, v54
	v_fmac_f32_e32 v177, v56, v56
	v_add_f32_e32 v176, v176, v177
	v_add_f32_e32 v163, v163, v176
	s_waitcnt vmcnt(0)
	v_pk_add_f32 v[52:53], v[52:53], v[214:215]
	v_pk_add_f32 v[50:51], v[50:51], v[212:213]
	v_mul_f32_e32 v177, v53, v53
	v_mul_f32_e32 v176, v51, v51
	v_fmac_f32_e32 v176, v50, v50
	v_fmac_f32_e32 v177, v52, v52
	v_add_f32_e32 v176, v176, v177
	v_add_f32_e32 v163, v163, v176
	ds_bpermute_b32 v176, v200, v163
	s_waitcnt lgkmcnt(0)
	v_add_f32_e32 v163, v163, v176
	ds_bpermute_b32 v176, v201, v163
	s_and_saveexec_b64 s[0:1], s[4:5]
	s_cbranch_execz .LBB0_976
	v_readlane_b32 s12, v253, 30
	v_readlane_b32 s13, v253, 31
	s_waitcnt lgkmcnt(0)
	v_add_f32_e32 v163, v163, v176
	v_lshl_add_u64 v[174:175], v[174:175], 2, s[12:13]
	v_mov_b32_e32 v216, v163
.LBB0_976:
	s_or_b64 exec, exec, s[0:1]
	s_waitcnt lgkmcnt(0)
	v_add_u32_e32 v176, 0x90, v162
	v_ashrrev_i32_e32 v177, 31, v176
	v_lshlrev_b64 v[174:175], 13, v[176:177]
	v_lshl_add_u64 v[174:175], s[58:59], 0, v[174:175]
	v_lshl_add_u64 v[174:175], v[154:155], 2, v[174:175]
	global_load_dwordx4 v[178:181], v[174:175], off
	global_load_dwordx4 v[204:207], v[174:175], off offset:64
	global_load_dwordx4 v[208:211], v[174:175], off offset:512
	global_load_dwordx4 v[212:215], v[174:175], off offset:576
	s_waitcnt vmcnt(3)
	v_pk_add_f32 v[48:49], v[48:49], v[180:181]
	v_pk_add_f32 v[46:47], v[46:47], v[178:179]
	v_mul_f32_e32 v178, v49, v49
	v_mul_f32_e32 v163, v47, v47
	v_fmac_f32_e32 v163, v46, v46
	v_fmac_f32_e32 v178, v48, v48
	v_add_f32_e32 v163, v163, v178
	s_waitcnt vmcnt(2)
	v_pk_add_f32 v[44:45], v[44:45], v[206:207]
	v_pk_add_f32 v[42:43], v[42:43], v[204:205]
	v_mul_f32_e32 v179, v45, v45
	v_mul_f32_e32 v178, v43, v43
	v_fmac_f32_e32 v178, v42, v42
	v_fmac_f32_e32 v179, v44, v44
	v_add_f32_e32 v178, v178, v179
	v_add_f32_e32 v163, v163, v178
	s_waitcnt vmcnt(1)
	v_pk_add_f32 v[40:41], v[40:41], v[210:211]
	v_pk_add_f32 v[38:39], v[38:39], v[208:209]
	v_mul_f32_e32 v179, v41, v41
	v_mul_f32_e32 v178, v39, v39
	v_fmac_f32_e32 v178, v38, v38
	v_fmac_f32_e32 v179, v40, v40
	v_add_f32_e32 v178, v178, v179
	v_add_f32_e32 v163, v163, v178
	s_waitcnt vmcnt(0)
	v_pk_add_f32 v[36:37], v[36:37], v[214:215]
	v_pk_add_f32 v[34:35], v[34:35], v[212:213]
	v_mul_f32_e32 v179, v37, v37
	v_mul_f32_e32 v178, v35, v35
	v_fmac_f32_e32 v178, v34, v34
	v_fmac_f32_e32 v179, v36, v36
	v_add_f32_e32 v178, v178, v179
	v_add_f32_e32 v163, v163, v178
	ds_bpermute_b32 v178, v200, v163
	s_waitcnt lgkmcnt(0)
	v_add_f32_e32 v163, v163, v178
	ds_bpermute_b32 v178, v201, v163
	s_and_saveexec_b64 s[0:1], s[4:5]
	s_cbranch_execz .LBB0_978
	v_readlane_b32 s12, v253, 30
	v_readlane_b32 s13, v253, 31
	s_waitcnt lgkmcnt(0)
	v_add_f32_e32 v163, v163, v178
	v_lshl_add_u64 v[176:177], v[176:177], 2, s[12:13]
	v_mov_b32_e32 v217, v163
;     __device__ __forceinline__ void operator()(f32x4 (&acc)[2][2][4][2], const Unit& u, int wr, int wc, int fr, int fq) const {
;     ...
;             for (int m = 0; m < 4; ++m) { const int row = row0 + ai * HALF + m * 16; const size_t off = (size_t)row * 2048 + col0; float ss = 0.f;
; #pragma unroll
;                 for (int bj = 0; bj < 2; ++bj)
; #pragma unroll
;                     for (int n = 0; n < 2; ++n) { const f32x4 xo = *(const f32x4*)(Xin + off + bj * HALF + n * 16) + acc[ai][bj][m][n]; acc[ai][bj][m][n] = xo;
;                         if (!FINAL) *(f32x4*)(X + off + bj * HALF + n * 16) = xo;
;                         ss += (xo[0] * xo[0] + xo[1] * xo[1]) + (xo[2] * xo[2] + xo[3] * xo[3]); }
;                 ss += __shfl_xor(ss, 16); ss += __shfl_xor(ss, 32);
;                 if (fq == 0) atomicAdd(ssq + row, ss); }
;         asm volatile("s_waitcnt vmcnt(0)" ::: "memory");
;         __builtin_amdgcn_s_barrier();
;         if (threadIdx.x == 0) { unsigned* c = cnt + 64 * u.pm; __hip_atomic_fetch_add(c, 1u, __ATOMIC_RELAXED, __HIP_MEMORY_SCOPE_AGENT);
.LBB0_978:
	s_or_b64 exec, exec, s[0:1]
	s_waitcnt lgkmcnt(0)
	v_add_u32_e32 v178, 0xa0, v162
	v_ashrrev_i32_e32 v179, 31, v178
	v_lshlrev_b64 v[176:177], 13, v[178:179]
	v_lshl_add_u64 v[176:177], s[58:59], 0, v[176:177]
	v_lshl_add_u64 v[176:177], v[154:155], 2, v[176:177]
	global_load_dwordx4 v[180:183], v[176:177], off
	global_load_dwordx4 v[204:207], v[176:177], off offset:64
	global_load_dwordx4 v[208:211], v[176:177], off offset:512
	global_load_dwordx4 v[212:215], v[176:177], off offset:576
	s_waitcnt vmcnt(3)
	v_pk_add_f32 v[32:33], v[32:33], v[182:183]
	v_pk_add_f32 v[30:31], v[30:31], v[180:181]
	v_mul_f32_e32 v180, v33, v33
	v_mul_f32_e32 v163, v31, v31
	v_fmac_f32_e32 v163, v30, v30
	v_fmac_f32_e32 v180, v32, v32
	v_add_f32_e32 v163, v163, v180
	s_waitcnt vmcnt(2)
	v_pk_add_f32 v[28:29], v[28:29], v[206:207]
	v_pk_add_f32 v[26:27], v[26:27], v[204:205]
	v_mul_f32_e32 v181, v29, v29
	v_mul_f32_e32 v180, v27, v27
	v_fmac_f32_e32 v180, v26, v26
	v_fmac_f32_e32 v181, v28, v28
	v_add_f32_e32 v180, v180, v181
	v_add_f32_e32 v163, v163, v180
	s_waitcnt vmcnt(1)
	v_pk_add_f32 v[24:25], v[24:25], v[210:211]
	v_pk_add_f32 v[22:23], v[22:23], v[208:209]
	v_mul_f32_e32 v181, v25, v25
	v_mul_f32_e32 v180, v23, v23
	v_fmac_f32_e32 v180, v22, v22
	v_fmac_f32_e32 v181, v24, v24
	v_add_f32_e32 v180, v180, v181
	v_add_f32_e32 v163, v163, v180
	s_waitcnt vmcnt(0)
	v_pk_add_f32 v[20:21], v[20:21], v[214:215]
	v_pk_add_f32 v[18:19], v[18:19], v[212:213]
	v_mul_f32_e32 v181, v21, v21
	v_mul_f32_e32 v180, v19, v19
	v_fmac_f32_e32 v180, v18, v18
	v_fmac_f32_e32 v181, v20, v20
	v_add_f32_e32 v180, v180, v181
	v_add_f32_e32 v163, v163, v180
	ds_bpermute_b32 v180, v200, v163
	s_waitcnt lgkmcnt(0)
	v_add_f32_e32 v163, v163, v180
	ds_bpermute_b32 v180, v201, v163
	s_and_saveexec_b64 s[0:1], s[4:5]
	s_cbranch_execz .LBB0_980
	v_readlane_b32 s12, v253, 30
	v_readlane_b32 s13, v253, 31
	s_waitcnt lgkmcnt(0)
	v_add_f32_e32 v163, v163, v180
	v_lshl_add_u64 v[178:179], v[178:179], 2, s[12:13]
	v_mov_b32_e32 v218, v163
.LBB0_980:
	s_or_b64 exec, exec, s[0:1]
	v_add_u32_e32 v194, 0xb0, v162
	v_ashrrev_i32_e32 v195, 31, v194
	v_lshlrev_b64 v[162:163], 13, v[194:195]
	v_lshl_add_u64 v[162:163], s[58:59], 0, v[162:163]
	v_lshl_add_u64 v[162:163], v[154:155], 2, v[162:163]
	s_waitcnt lgkmcnt(0)
	global_load_dwordx4 v[180:183], v[162:163], off
	global_load_dwordx4 v[204:207], v[162:163], off offset:64
	global_load_dwordx4 v[208:211], v[162:163], off offset:512
	global_load_dwordx4 v[212:215], v[162:163], off offset:576
	s_waitcnt vmcnt(3)
	v_pk_add_f32 v[178:179], v[16:17], v[182:183]
	v_pk_add_f32 v[180:181], v[14:15], v[180:181]
	v_mul_f32_e32 v15, v179, v179
	v_mul_f32_e32 v14, v181, v181
	v_fmac_f32_e32 v14, v180, v180
	v_fmac_f32_e32 v15, v178, v178
	v_add_f32_e32 v186, v14, v15
	s_waitcnt vmcnt(2)
	v_pk_add_f32 v[182:183], v[12:13], v[206:207]
	v_pk_add_f32 v[184:185], v[10:11], v[204:205]
	v_mul_f32_e32 v11, v183, v183
	v_mul_f32_e32 v10, v185, v185
	v_fmac_f32_e32 v10, v184, v184
	v_fmac_f32_e32 v11, v182, v182
	v_add_f32_e32 v10, v10, v11
	v_add_f32_e32 v14, v186, v10
	s_waitcnt vmcnt(1)
	v_pk_add_f32 v[186:187], v[8:9], v[210:211]
	v_pk_add_f32 v[188:189], v[6:7], v[208:209]
	v_mul_f32_e32 v7, v187, v187
	v_mul_f32_e32 v6, v189, v189
	v_fmac_f32_e32 v6, v188, v188
	v_fmac_f32_e32 v7, v186, v186
	v_add_f32_e32 v6, v6, v7
	v_add_f32_e32 v10, v14, v6
	s_waitcnt vmcnt(0)
	v_pk_add_f32 v[190:191], v[4:5], v[214:215]
	v_pk_add_f32 v[192:193], v[2:3], v[212:213]
	v_mul_f32_e32 v3, v191, v191
	v_mul_f32_e32 v2, v193, v193
	v_fmac_f32_e32 v2, v192, v192
	v_fmac_f32_e32 v3, v190, v190
	v_add_f32_e32 v2, v2, v3
	v_add_f32_e32 v2, v10, v2
	ds_bpermute_b32 v3, v200, v2
	s_waitcnt lgkmcnt(0)
	v_add_f32_e32 v2, v2, v3
	ds_bpermute_b32 v3, v201, v2
	s_and_saveexec_b64 s[0:1], s[4:5]
	s_cbranch_execz .LBB0_982
	v_readlane_b32 s12, v253, 30
	v_readlane_b32 s13, v253, 31
	s_waitcnt lgkmcnt(0)
	v_add_f32_e32 v2, v2, v3
	v_lshl_add_u64 v[4:5], v[194:195], 2, s[12:13]
	v_mov_b32_e32 v219, v2
.LBB0_982:
	s_or_b64 exec, exec, s[0:1]
	s_and_saveexec_b64 s[0:1], s[4:5]
	global_atomic_add_f32 v[114:115], v216, off offset:512
	global_atomic_add_f32 v[114:115], v217, off offset:576
	global_atomic_add_f32 v[114:115], v218, off offset:640
	global_atomic_add_f32 v[114:115], v219, off offset:704
	s_or_b64 exec, exec, s[0:1]
	s_waitcnt vmcnt(0)
	s_barrier
	s_mov_b64 s[0:1], exec
	v_readlane_b32 s12, v253, 7
	v_readlane_b32 s13, v253, 8
	s_and_b64 s[12:13], s[0:1], s[12:13]
	s_mov_b64 exec, s[12:13]
	s_cbranch_execz .LBB0_997
	s_lshl_b32 s12, s28, 6
	s_mov_b64 s[26:27], exec
	s_ashr_i32 s13, s12, 31
	s_lshl_b64 s[12:13], s[12:13], 2
	v_mbcnt_lo_u32_b32 v2, s26, 0
	s_add_u32 s24, s84, s12
	v_mbcnt_hi_u32_b32 v2, s27, v2
	s_addc_u32 s25, s85, s13
	v_cmp_eq_u32_e32 vcc, 0, v2
	s_and_saveexec_b64 s[28:29], vcc
	s_cbranch_execz .LBB0_985
	s_bcnt1_i32_b64 s12, s[26:27]
	v_mov_b32_e32 v2, s12
	global_atomic_add v1, v2, s[24:25]
